# pass-1 GLA unit: the 16 V^T-image loads are issued first at the top of the unit (they used to be issued only after the gate-log cumsum had consumed the first batch of loads)
# speedup vs baseline: 1.0049x; 1.0025x over previous
; template <int PASS>
; __device__ __forceinline__ void gla_unit(LAS unsigned char* lds, int ch, int h, const bf16* PROJ, const bf16* GT, bf16* STG, float* DECG, bf16* OMIX, const float* gla_norm) {
;     ...
;         const int kk = tid & 63, qt = (tid >> 6) & 3, d = tid >> 8;
;         const bf16* gp = GT + ((size_t)d * MALL + m0 + 16 * qt) * 256 + h * 64 + kk;
;         const bf16* qp = PROJ + (m0 + 16 * qt) * LDP + PQ + h * 64 + kk; const bf16* kp = PROJ + (m0 + 16 * qt) * LDP + PK + h * 64 + kk;
;         float c[16], kv[16], qv[16];
; #pragma unroll
;         for (int jj = 0; jj < 16; ++jj) { c[jj] = bf1(gp[(size_t)jj * 256]); kv[jj] = bf1(kp[(size_t)jj * LDP]); if (PASS == 1) qv[jj] = bf1(qp[(size_t)jj * LDP]); }
;     ...
;         { const int vcol = tid & 127, q4 = tid >> 7; const bf16* vp = PROJ + (m0 + 16 * q4) * LDP + PV + h * 128 + vcol; unsigned vv[16];
; #pragma unroll
;           for (int jj = 0; jj < 16; ++jj) vv[jj] = vp[(size_t)jj * LDP];
.LBB0_760:
	s_ashr_i32 s46, s82, 2
	v_mov_b32_e32 v114, v0
	s_ashr_i32 s47, s46, 31
	s_waitcnt vmcnt(1)
	v_ashrrev_i32_e32 v20, 6, v114
	v_ashrrev_i32_e32 v55, 8, v114
	s_lshl_b64 s[44:45], s[46:47], 6
	v_ashrrev_i32_e32 v158, 7, v114
	v_lshlrev_b32_e32 v224, 4, v158
	v_ashrrev_i32_e32 v225, 31, v224
	v_lshl_add_u64 v[224:225], s[44:45], 0, v[224:225]
	v_mov_b64_e32 v[226:227], s[42:43]
	v_and_b32_e32 v159, 0x7f, v114
	v_mad_u64_u32 v[226:227], s[100:101], v224, s35, v[226:227]
	v_mad_i32_i24 v227, v225, s35, v227
	v_lshlrev_b32_e32 v224, 1, v159
	v_mov_b32_e32 v225, v93
	v_lshl_add_u64 v[224:225], v[226:227], 0, v[224:225]
	v_add_co_u32_e64 v226, s[98:99], s52, v224
	s_nop 0
	s_nop 0
	v_addc_co_u32_e64 v227, s[98:99], 0, v225, s[98:99]
	v_add_co_u32_e64 v228, s[98:99], s71, v224
	s_nop 0
	s_nop 0
	v_addc_co_u32_e64 v229, s[98:99], 0, v225, s[98:99]
	v_add_co_u32_e64 v230, s[98:99], s54, v224
	s_nop 0
	s_nop 0
	v_addc_co_u32_e64 v231, s[98:99], 0, v225, s[98:99]
	v_add_co_u32_e64 v232, s[98:99], s55, v224
	s_nop 0
	s_nop 0
	v_addc_co_u32_e64 v233, s[98:99], 0, v225, s[98:99]
	v_add_co_u32_e64 v234, s[98:99], s56, v224
	s_nop 0
	s_nop 0
	v_addc_co_u32_e64 v235, s[98:99], 0, v225, s[98:99]
	v_add_co_u32_e64 v236, s[98:99], s57, v224
	s_nop 1
	v_addc_co_u32_e64 v237, s[98:99], 0, v225, s[98:99]
	v_add_co_u32_e64 v238, s[98:99], s72, v224
	s_nop 1
	v_addc_co_u32_e64 v239, s[98:99], 0, v225, s[98:99]
	global_load_ushort v160, v[224:225], off offset:1024
	global_load_ushort v161, v[226:227], off offset:2688
	global_load_ushort v162, v[228:229], off offset:256
	global_load_ushort v163, v[230:231], off offset:1920
	global_load_ushort v164, v[232:233], off offset:3584
	global_load_ushort v165, v[234:235], off offset:1152
	global_load_ushort v166, v[236:237], off offset:2816
	global_load_ushort v167, v[238:239], off offset:384
	v_add_co_u32_e64 v226, s[98:99], s59, v224
	s_nop 1
	v_addc_co_u32_e64 v227, s[98:99], 0, v225, s[98:99]
	v_add_co_u32_e64 v228, s[98:99], s60, v224
	s_nop 1
	v_addc_co_u32_e64 v229, s[98:99], 0, v225, s[98:99]
	v_add_co_u32_e64 v230, s[98:99], s61, v224
	s_nop 1
	v_addc_co_u32_e64 v231, s[98:99], 0, v225, s[98:99]
	v_add_co_u32_e64 v232, s[98:99], s62, v224
	s_nop 1
	v_addc_co_u32_e64 v233, s[98:99], 0, v225, s[98:99]
	v_add_co_u32_e64 v234, s[98:99], s63, v224
	s_nop 1
	v_addc_co_u32_e64 v235, s[98:99], 0, v225, s[98:99]
	v_add_co_u32_e64 v236, s[98:99], s65, v224
	s_nop 1
	v_addc_co_u32_e64 v237, s[98:99], 0, v225, s[98:99]
	v_add_co_u32_e64 v238, s[98:99], s66, v224
	s_nop 1
	v_addc_co_u32_e64 v239, s[98:99], 0, v225, s[98:99]
	v_add_co_u32_e64 v224, s[98:99], s67, v224
	s_nop 1
	v_addc_co_u32_e64 v225, s[98:99], 0, v225, s[98:99]
	global_load_ushort v168, v[226:227], off offset:2048
	s_nop 0
	global_load_ushort v169, v[228:229], off offset:3712
	s_nop 0
	global_load_ushort v170, v[230:231], off offset:1280
	s_nop 0
	global_load_ushort v171, v[232:233], off offset:2944
	global_load_ushort v172, v[234:235], off offset:512
	s_nop 0
	global_load_ushort v173, v[236:237], off offset:2176
	global_load_ushort v174, v[238:239], off offset:3840
	global_load_ushort v175, v[224:225], off offset:1408
	v_and_b32_e32 v36, 3, v20
	v_mul_hi_i32_i24_e32 v3, 0x4400, v55
	v_mul_i32_i24_e32 v2, 0x4400, v55
	v_lshl_add_u64 v[2:3], v[2:3], 0, s[44:45]
	v_lshlrev_b32_e32 v4, 4, v36
	v_or_b32_e32 v2, v2, v4
	v_or_b32_e32 v4, s44, v4
	v_and_b32_e32 v113, 63, v114
	v_mad_u64_u32 v[4:5], s[0:1], v4, s35, v[94:95]
	v_lshlrev_b32_e32 v92, 1, v113
	v_mad_i32_i24 v5, s45, v1, v5
	v_lshl_add_u64 v[4:5], v[4:5], 0, v[92:93]
	v_add_co_u32_e32 v6, vcc, s52, v4
	v_lshlrev_b64 v[2:3], 9, v[2:3]
	s_nop 0
	v_addc_co_u32_e32 v7, vcc, 0, v5, vcc
	v_add_co_u32_e32 v8, vcc, s53, v4
	v_lshl_add_u64 v[2:3], s[36:37], 0, v[2:3]
	s_nop 0
	v_addc_co_u32_e32 v9, vcc, 0, v5, vcc
	v_add_co_u32_e32 v10, vcc, s54, v4
	v_lshl_add_u64 v[2:3], v[2:3], 0, v[92:93]
	s_nop 0
	v_addc_co_u32_e32 v11, vcc, 0, v5, vcc
	global_load_ushort v41, v[4:5], off offset:512
	global_load_ushort v38, v[6:7], off offset:2176
	global_load_ushort v37, v[8:9], off offset:3840
	global_load_ushort v39, v[10:11], off offset:1408
	global_load_ushort v40, v[10:11], off offset:896
	global_load_ushort v42, v[8:9], off offset:3328
	global_load_ushort v43, v[6:7], off offset:1664
	global_load_ushort v44, v[4:5], off
	v_add_co_u32_e32 v6, vcc, s55, v4
	v_readfirstlane_b32 s47, v20
	s_nop 0
	v_addc_co_u32_e32 v7, vcc, 0, v5, vcc
	v_add_co_u32_e32 v8, vcc, s56, v4
	v_cmp_gt_u32_e64 s[4:5], s69, v114
	s_nop 0
	v_addc_co_u32_e32 v9, vcc, 0, v5, vcc
	v_add_co_u32_e32 v10, vcc, s57, v4
	s_nop 1
	v_addc_co_u32_e32 v11, vcc, 0, v5, vcc
	v_add_co_u32_e32 v12, vcc, s58, v4
	s_nop 1
	v_addc_co_u32_e32 v13, vcc, 0, v5, vcc
	global_load_ushort v49, v[6:7], off offset:3072
	global_load_ushort v46, v[8:9], off offset:640
	global_load_ushort v45, v[10:11], off offset:2304
	global_load_ushort v47, v[12:13], off offset:3968
	global_load_ushort v48, v[12:13], off offset:3456
	global_load_ushort v50, v[10:11], off offset:1792
	global_load_ushort v51, v[8:9], off offset:128
	global_load_ushort v52, v[6:7], off offset:2560
	global_load_ushort v21, v[2:3], off
	global_load_ushort v22, v[2:3], off offset:512
	global_load_ushort v23, v[2:3], off offset:1024
	global_load_ushort v24, v[2:3], off offset:1536
	global_load_ushort v26, v[2:3], off offset:2048
	global_load_ushort v27, v[2:3], off offset:2560
	global_load_ushort v28, v[2:3], off offset:3072
	global_load_ushort v29, v[2:3], off offset:3584
	v_add_co_u32_e32 v6, vcc, s59, v4
	s_waitcnt vmcnt(4)
; template <int PASS>
; __device__ __forceinline__ void gla_unit(LAS unsigned char* lds, int ch, int h, const bf16* PROJ, const bf16* GT, bf16* STG, float* DECG, bf16* OMIX, const float* gla_norm) {
;     ...
;         for (int jj = 0; jj < 16; ++jj) { c[jj] = bf1(gp[(size_t)jj * 256]); kv[jj] = bf1(kp[(size_t)jj * LDP]); if (PASS == 1) qv[jj] = bf1(qp[(size_t)jj * LDP]); }
;         if (d == 0) {
; #pragma unroll
;             for (int jj = 1; jj < 16; ++jj) c[jj] += c[jj - 1];
;         } else {
; #pragma unroll
	v_lshlrev_b32_e32 v25, 16, v24
	v_addc_co_u32_e32 v7, vcc, 0, v5, vcc
	v_add_co_u32_e32 v2, vcc, s52, v2
	v_lshlrev_b32_e32 v24, 16, v23
	s_nop 0
	v_addc_co_u32_e32 v3, vcc, 0, v3, vcc
	global_load_ushort v53, v[6:7], off offset:1536
	global_load_ushort v30, v[2:3], off
	global_load_ushort v31, v[2:3], off offset:512
	global_load_ushort v32, v[2:3], off offset:1024
	global_load_ushort v33, v[2:3], off offset:1536
	global_load_ushort v34, v[2:3], off offset:2048
	global_load_ushort v35, v[2:3], off offset:2560
	global_load_ushort v54, v[6:7], off offset:1024
	v_add_co_u32_e32 v6, vcc, s60, v4
	s_waitcnt vmcnt(10)
	v_lshlrev_b32_e32 v27, 16, v27
	v_addc_co_u32_e32 v7, vcc, 0, v5, vcc
	v_add_co_u32_e32 v8, vcc, s61, v4
	v_lshlrev_b32_e32 v26, 16, v26
	s_nop 0
	v_addc_co_u32_e32 v9, vcc, 0, v5, vcc
	v_add_co_u32_e32 v10, vcc, s62, v4
	s_waitcnt vmcnt(8)
	v_lshlrev_b32_e32 v29, 16, v29
	v_addc_co_u32_e32 v11, vcc, 0, v5, vcc
	v_add_co_u32_e32 v12, vcc, s63, v4
	global_load_ushort v59, v[6:7], off offset:3200
	global_load_ushort v58, v[8:9], off offset:768
	global_load_ushort v56, v[10:11], off offset:2432
	global_load_ushort v57, v[10:11], off offset:1920
	global_load_ushort v60, v[8:9], off offset:256
	global_load_ushort v61, v[6:7], off offset:2688
	s_nop 0
	global_load_ushort v6, v[2:3], off offset:3072
	global_load_ushort v7, v[2:3], off offset:3584
	v_addc_co_u32_e32 v13, vcc, 0, v5, vcc
	v_add_co_u32_e32 v14, vcc, s64, v4
	v_lshlrev_b32_e32 v28, 16, v28
	s_nop 0
	v_addc_co_u32_e32 v15, vcc, 0, v5, vcc
	v_add_co_u32_e32 v16, vcc, s65, v4
	s_waitcnt vmcnt(14)
	v_lshlrev_b32_e32 v30, 16, v30
	v_addc_co_u32_e32 v17, vcc, 0, v5, vcc
	v_add_co_u32_e32 v18, vcc, s66, v4
	s_waitcnt vmcnt(13)
	v_lshlrev_b32_e32 v31, 16, v31
	v_addc_co_u32_e32 v19, vcc, 0, v5, vcc
	v_add_co_u32_e32 v2, vcc, 0x15000, v4
	s_waitcnt vmcnt(11)
	v_lshlrev_b32_e32 v33, 16, v33
	v_addc_co_u32_e32 v3, vcc, 0, v5, vcc
	global_load_ushort v66, v[12:13], off
	global_load_ushort v67, v[14:15], off offset:3584
	global_load_ushort v68, v[16:17], off offset:1664
	global_load_ushort v62, v[18:19], off offset:3328
	global_load_ushort v63, v[2:3], off offset:896
	global_load_ushort v64, v[2:3], off offset:384
	global_load_ushort v65, v[18:19], off offset:2816
	global_load_ushort v69, v[16:17], off offset:1152
	v_lshlrev_b32_e32 v19, 16, v22
	v_lshlrev_b32_e32 v18, 16, v21
	v_lshlrev_b32_e32 v32, 16, v32
	s_waitcnt vmcnt(17)
	v_lshlrev_b32_e32 v35, 16, v35
	v_lshlrev_b32_e32 v34, 16, v34
	v_cmp_lt_u32_e32 vcc, s68, v114
	s_waitcnt vmcnt(9)
	v_lshlrev_b32_e32 v82, 16, v6
	s_waitcnt vmcnt(8)
	v_lshlrev_b32_e32 v83, 16, v7
	s_and_saveexec_b64 s[0:1], s[4:5]
	s_xor_b64 s[0:1], exec, s[0:1]
	s_cbranch_execz .LBB0_762
	v_pk_add_f32 v[22:23], v[18:19], v[18:19] op_sel:[1,0] op_sel_hi:[0,1]
	v_pk_add_f32 v[20:21], v[22:23], v[24:25]
	s_nop 0
	v_pk_add_f32 v[16:17], v[20:21], v[24:25] op_sel:[0,1] op_sel_hi:[1,0]
	s_nop 0
	v_pk_add_f32 v[14:15], v[16:17], v[26:27]
	s_nop 0
	v_pk_add_f32 v[12:13], v[14:15], v[26:27] op_sel:[0,1] op_sel_hi:[1,0]
	s_nop 0
	v_pk_add_f32 v[10:11], v[12:13], v[28:29]
	s_nop 0
	v_pk_add_f32 v[8:9], v[10:11], v[28:29] op_sel:[0,1] op_sel_hi:[1,0]
	s_nop 0
	v_pk_add_f32 v[6:7], v[8:9], v[30:31]
	s_nop 0
	v_pk_add_f32 v[4:5], v[6:7], v[30:31] op_sel:[0,1] op_sel_hi:[1,0]
	s_nop 0
	v_pk_add_f32 v[2:3], v[4:5], v[32:33]
	s_nop 0
	v_pk_add_f32 v[90:91], v[2:3], v[32:33] op_sel:[0,1] op_sel_hi:[1,0]
	s_nop 0
	v_pk_add_f32 v[88:89], v[90:91], v[34:35]
	s_nop 0
	v_pk_add_f32 v[86:87], v[88:89], v[34:35] op_sel:[0,1] op_sel_hi:[1,0]
	s_nop 0
	v_pk_add_f32 v[84:85], v[86:87], v[82:83]
	s_nop 0
	v_pk_add_f32 v[24:25], v[84:85], v[82:83] op_sel:[0,1] op_sel_hi:[1,0]
	s_nop 0
	v_mov_b32_e32 v83, v24

; #define LAS __attribute__((address_space(3)))
; template <int PASS>
; __device__ __forceinline__ void gla_unit(LAS unsigned char* lds, int ch, int h, const bf16* PROJ, const bf16* GT, bf16* STG, float* DECG, bf16* OMIX, const float* gla_norm) {
;     ...
;         OFFS[(d * 4 + qt) * 64 + kk] = d ? c[0] : c[15];
;         { const int vcol = tid & 127, q4 = tid >> 7; const bf16* vp = PROJ + (m0 + 16 * q4) * LDP + PV + h * 128 + vcol; unsigned vv[16];
; #pragma unroll
;           for (int jj = 0; jj < 16; ++jj) vv[jj] = vp[(size_t)jj * LDP];
; #pragma unroll
;           for (int jj = 0; jj < 16; ++jj) asm volatile("" : "+v"(vv[jj]));
;           v4u w0, w1; w0.x = vv[0] | (vv[1] << 16); w0.y = vv[2] | (vv[3] << 16); w0.z = vv[4] | (vv[5] << 16); w0.w = vv[6] | (vv[7] << 16);
;           w1.x = vv[8] | (vv[9] << 16); w1.y = vv[10] | (vv[11] << 16); w1.z = vv[12] | (vv[13] << 16); w1.w = vv[14] | (vv[15] << 16);
;           *(LAS v4u*)(VT + vcol * RS + q4 * 32) = w0; *(LAS v4u*)(VT + vcol * RS + q4 * 32 + 16) = w1; }
;         __syncthreads();
;         float off = 0.f, tot = 0.f;
; #pragma unroll
;         for (int q2 = 0; q2 < 4; ++q2) { const float t = OFFS[(d * 4 + q2) * 64 + kk]; tot += t; if (d ? (q2 > qt) : (q2 < qt)) off += t; }
.LBB0_764:
	s_or_b64 exec, exec, s[0:1]
	v_ashrrev_i32_e32 v5, 7, v114
	v_lshlrev_b32_e32 v24, 4, v5
	v_ashrrev_i32_e32 v25, 31, v24
	v_lshl_add_u64 v[24:25], s[44:45], 0, v[24:25]
	v_mov_b64_e32 v[26:27], s[42:43]
	v_and_b32_e32 v3, 0x7f, v114
	v_mad_u64_u32 v[26:27], s[0:1], v24, s35, v[26:27]
	v_mad_i32_i24 v27, v25, s35, v27
	v_lshlrev_b32_e32 v24, 1, v3
	v_mov_b32_e32 v25, v93
	v_lshl_add_u64 v[24:25], v[26:27], 0, v[24:25]
	v_add_co_u32_e64 v26, s[6:7], s52, v24
	v_lshlrev_b32_e32 v115, 2, v113
	s_nop 0
	v_addc_co_u32_e64 v27, s[6:7], 0, v25, s[6:7]
	v_add_co_u32_e64 v28, s[6:7], s71, v24
	v_mul_u32_u24_e32 v3, 0x90, v3
	s_nop 0
	v_addc_co_u32_e64 v29, s[6:7], 0, v25, s[6:7]
	v_add_co_u32_e64 v30, s[6:7], s54, v24
	v_lshlrev_b32_e32 v5, 5, v5
	s_nop 0
	v_addc_co_u32_e64 v31, s[6:7], 0, v25, s[6:7]
	v_add_co_u32_e64 v32, s[6:7], s55, v24
	v_add3_u32 v3, 0, v3, v5
	s_nop 0
	v_addc_co_u32_e64 v33, s[6:7], 0, v25, s[6:7]
	v_add_co_u32_e64 v34, s[6:7], s56, v24
	s_mov_b64 s[0:1], 0
	s_nop 0
	v_addc_co_u32_e64 v35, s[6:7], 0, v25, s[6:7]
	v_add_co_u32_e64 v70, s[6:7], s57, v24
	s_nop 1
	v_addc_co_u32_e64 v71, s[6:7], 0, v25, s[6:7]
	v_add_co_u32_e64 v72, s[6:7], s72, v24
	s_nop 1
	v_addc_co_u32_e64 v73, s[6:7], 0, v25, s[6:7]
	v_mov_b32_e32 v7, v160
	v_mov_b32_e32 v9, v161
	v_mov_b32_e32 v11, v162
	v_mov_b32_e32 v13, v163
	v_mov_b32_e32 v15, v164
	v_mov_b32_e32 v17, v165
	v_mov_b32_e32 v19, v166
	v_mov_b32_e32 v21, v167
	v_add_co_u32_e64 v26, s[6:7], s59, v24
	s_nop 1
	v_addc_co_u32_e64 v27, s[6:7], 0, v25, s[6:7]
	v_add_co_u32_e64 v28, s[6:7], s60, v24
	s_nop 1
	v_addc_co_u32_e64 v29, s[6:7], 0, v25, s[6:7]
	v_add_co_u32_e64 v30, s[6:7], s61, v24
	s_nop 1
	v_addc_co_u32_e64 v31, s[6:7], 0, v25, s[6:7]
	v_add_co_u32_e64 v32, s[6:7], s62, v24
	s_nop 1
	v_addc_co_u32_e64 v33, s[6:7], 0, v25, s[6:7]
	v_add_co_u32_e64 v34, s[6:7], s63, v24
	s_nop 1
	v_addc_co_u32_e64 v35, s[6:7], 0, v25, s[6:7]
	v_add_co_u32_e64 v70, s[6:7], s65, v24
	s_nop 1
	v_addc_co_u32_e64 v71, s[6:7], 0, v25, s[6:7]
	v_add_co_u32_e64 v72, s[6:7], s66, v24
	s_nop 1
	v_addc_co_u32_e64 v73, s[6:7], 0, v25, s[6:7]
	v_add_co_u32_e64 v24, s[6:7], s67, v24
	s_nop 1
	v_addc_co_u32_e64 v25, s[6:7], 0, v25, s[6:7]
	v_mov_b32_e32 v23, v168
	s_nop 0
	v_mov_b32_e32 v28, v169
	s_nop 0
	v_mov_b32_e32 v29, v170
	s_nop 0
	v_mov_b32_e32 v30, v171
	v_mov_b32_e32 v31, v172
	s_nop 0
	v_mov_b32_e32 v32, v173
	v_mov_b32_e32 v33, v174
	v_mov_b32_e32 v34, v175
	v_lshlrev_b32_e32 v35, 10, v55
	v_lshlrev_b32_e32 v25, 8, v36
	v_add_u32_e32 v26, s70, v35
	v_cndmask_b32_e32 v24, v83, v18, vcc
	v_add3_u32 v25, v26, v25, v115
	ds_write_b32 v25, v24
	s_waitcnt vmcnt(15)
	s_waitcnt vmcnt(14)
	s_waitcnt vmcnt(13)
	s_waitcnt vmcnt(12)
	s_waitcnt vmcnt(11)
	s_waitcnt vmcnt(10)
	s_waitcnt vmcnt(9)
	s_waitcnt vmcnt(8)
	s_waitcnt vmcnt(7)
	s_waitcnt vmcnt(6)
	s_waitcnt vmcnt(5)
	s_waitcnt vmcnt(4)
	s_waitcnt vmcnt(3)
	v_lshl_or_b32 v24, v9, 16, v7
	v_lshl_or_b32 v25, v13, 16, v11
	v_lshl_or_b32 v26, v17, 16, v15
	v_lshl_or_b32 v27, v21, 16, v19
	s_waitcnt vmcnt(2)
	s_waitcnt vmcnt(1)
	s_waitcnt vmcnt(0)
	v_lshl_or_b32 v28, v28, 16, v23
	v_lshl_or_b32 v29, v30, 16, v29
	v_lshl_or_b32 v30, v32, 16, v31
	v_lshl_or_b32 v31, v34, 16, v33
	ds_write_b128 v3, v[24:27] offset:55296
	ds_write_b128 v3, v[28:31] offset:55312
	v_add_u32_e32 v3, s70, v115
	v_add_u32_e32 v3, v3, v35
	s_waitcnt lgkmcnt(0)
	s_barrier
	ds_read2st64_b32 v[24:25], v3 offset1:1
	v_cmp_eq_u32_e64 s[6:7], 0, v36
	s_and_saveexec_b64 s[8:9], s[4:5]
	s_xor_b64 s[12:13], exec, s[8:9]
	v_cmp_lt_u32_e64 s[8:9], 1, v36
	s_and_b64 s[0:1], s[8:9], exec
	s_or_saveexec_b64 s[8:9], s[12:13]
	s_waitcnt lgkmcnt(0)
	v_add_f32_e32 v5, 0, v24
	s_or_b64 s[12:13], vcc, s[6:7]
	v_cndmask_b32_e64 v7, v5, 0, s[12:13]
	v_mov_b32_e32 v5, v7
	s_xor_b64 exec, exec, s[8:9]
	s_andn2_b64 s[0:1], s[0:1], exec
	s_and_b64 s[6:7], s[6:7], exec
	v_mov_b32_e32 v5, 0
	s_or_b64 s[0:1], s[0:1], s[6:7]
	s_or_b64 exec, exec, s[8:9]
	s_and_saveexec_b64 s[6:7], s[0:1]
	v_add_f32_e32 v5, v25, v7
	s_or_b64 exec, exec, s[6:7]
	ds_read_b32 v7, v3 offset:512
	s_mov_b64 s[0:1], 0
	v_cmp_eq_u32_e64 s[6:7], 3, v36
	s_and_saveexec_b64 s[8:9], s[4:5]
	s_xor_b64 s[4:5], exec, s[8:9]
	s_cbranch_execnz .LBB0_784
	s_andn2_saveexec_b64 s[6:7], s[4:5]
	s_cbranch_execnz .LBB0_785
